# v022 plus weight-conversion split moved: phase 0 converts 9536 items, each of the three FFN-up phases 10496 (was 13424 / 9200)
# baseline (speedup 1.0000x reference)
; #define LAS __attribute__((address_space(3)))
; DI void convert_range(const Args& a, LAS unsigned char* lds, int lo_, int hi_, int blk, int nblk, int wave, int lane, bool with_x) {
;     const int chunk = (((hi_ - lo_) + nblk - 1) / nblk + 7) & ~7;
;     const int lo = lo_ + blk * chunk - wave, hi = (lo_ + (blk + 1) * chunk) < hi_ ? (lo_ + (blk + 1) * chunk) : hi_;
; __global__ void __launch_bounds__(NTHREADS, 2) mega_fwd(Args a) {
;     ...
;     int cv = bid; bool grouped = false;
;     unsigned char* ws = a.ws;
;     bf16_t* XB = (bf16_t*)(ws + WS_XB); float* Y = (float*)(ws + WS_Y); bf16_t* BIG = (bf16_t*)(ws + WS_BIG);
;     bf16_t* DP = (bf16_t*)(ws + WS_DP); bf16_t* CAT = (bf16_t*)(ws + WS_CAT); bf16_t* VT = (bf16_t*)(ws + WS_VT);
;     float* X = a.out;
;     volatile LAS unsigned* misc = (volatile LAS unsigned*)(lds + MISC_OFF);
;     if (threadIdx.x < 16) misc[threadIdx.x] = 0u;
;     __syncthreads();
;     XcdBarrier xbar; xbar.bar = (unsigned*)(ws + WS_CTL); xbar.x = 0; xbar.st = misc;
;     if (a.ph_hi - a.ph_lo > 1) xbar = xcd_barrier_post((unsigned*)(ws + WS_CTL), misc);
.LBB0_8:
	s_cmp_le_i32 s95, s94
	s_cbranch_scc1 .LBB0_651
	s_add_u32 s4, s92, 0x18080000
	s_addc_u32 s5, s93, 0
	v_writelane_b32 v253, s4, 11
	s_load_dwordx16 s[56:71], s[0:1], 0x0
	v_mbcnt_lo_u32_b32 v190, -1, 0
	v_writelane_b32 v253, s5, 12
	s_add_u32 s4, s92, 0x14080000
	s_addc_u32 s5, s93, 0
	s_add_u32 s84, s92, 0x1a080000
	s_addc_u32 s85, s93, 0
	s_add_u32 s86, s92, 0x21080000
	v_writelane_b32 v253, s4, 13
	s_addc_u32 s87, s93, 0
	v_mov_b32_e32 v97, 0
	v_writelane_b32 v253, s5, 14
	s_add_u32 s4, s92, 0x1e080000
	s_addc_u32 s5, s93, 0
	v_writelane_b32 v253, s4, 15
	v_mov_b32_e32 v189, 1
	v_mbcnt_hi_u32_b32 v191, -1, v190
	v_writelane_b32 v253, s5, 16
	s_add_u32 s4, s92, 0x11880000
	s_addc_u32 s5, s93, 0
	v_writelane_b32 v253, s4, 17
	v_mov_b32_e32 v248, 0xffffe000
	v_mov_b32_e32 v252, 0xffffc000
	v_writelane_b32 v253, s5, 18
	s_add_u32 s4, s92, 0x11800000
	s_addc_u32 s5, s93, 0
	s_add_u32 s96, s92, 0x10800000
	v_writelane_b32 v253, s4, 19
	s_addc_u32 s97, s93, 0
	s_add_u32 s3, s92, 0xb000000
	v_writelane_b32 v253, s5, 20
	v_writelane_b32 v253, s3, 21
	s_addc_u32 s3, s93, 0
	s_add_u32 s4, s92, 0x12080000
	v_writelane_b32 v253, s3, 22
	s_addc_u32 s5, s93, 0
	v_writelane_b32 v253, s4, 23
	v_mov_b32_e32 v250, 0xffffa000
	v_mov_b32_e32 v207, 0xffff8000
	v_writelane_b32 v253, s5, 24
	s_add_u32 s4, s92, 0x13880000
	s_addc_u32 s5, s93, 0
	v_writelane_b32 v253, s4, 25
	v_mov_b32_e32 v196, 0xffff6000
	v_mov_b32_e32 v197, 0xffff4000
	v_writelane_b32 v253, s5, 26
	s_add_u32 s4, s92, 0x23090000
	s_addc_u32 s5, s93, 0
	v_writelane_b32 v253, s4, 27
	s_lshl_b32 s3, s10, 9
	s_ashr_i32 s11, s10, 31
	v_writelane_b32 v253, s5, 28
	s_addk_i32 s3, 0xc000
	v_writelane_b32 v253, s3, 29
	s_add_u32 s3, s92, 0x23084000
	v_writelane_b32 v253, s3, 30
	s_addc_u32 s3, s93, 0
	s_cmpk_gt_i32 s10, 0xf0
	v_writelane_b32 v253, s3, 31
	s_cselect_b64 s[4:5], -1, 0
	s_cmpk_eq_i32 s10, 0x100
	v_writelane_b32 v253, s4, 32
	s_cselect_b64 s[8:9], -1, 0
	s_ashr_i32 s3, s2, 31
	v_writelane_b32 v253, s5, 33
	s_add_i32 s4, s10, 0x253f
	s_lshl_b64 s[98:99], s[10:11], 9
	s_lshl_b64 s[6:7], s[2:3], 9
	v_writelane_b32 v253, s6, 34
	s_cmp_lt_i32 s95, 16
	v_mov_b32_e32 v198, 0xffff2000
	v_writelane_b32 v253, s7, 35
	s_cselect_b64 s[6:7], -1, 0
	v_writelane_b32 v253, s6, 36
	v_mov_b32_e32 v199, 0xffff0000
	v_mov_b32_e32 v200, 0xfffee000
	v_writelane_b32 v253, s7, 37
	s_add_u32 s6, s92, 0x23080200
	s_addc_u32 s7, s93, 0
	v_writelane_b32 v253, s6, 38
	v_mov_b32_e32 v201, 0xfffec000
	v_mov_b32_e32 v202, 0xfffea000
	v_writelane_b32 v253, s7, 39
	s_add_u32 s6, s92, 0x23080400
	s_addc_u32 s7, s93, 0
	v_writelane_b32 v253, s6, 40
	v_mov_b32_e32 v203, 0xfffe8000
	v_mov_b32_e32 v204, 0xfffe6000
	v_writelane_b32 v253, s7, 41
	s_add_u32 s6, s92, 0x23080500
	s_addc_u32 s7, s93, 0
	v_writelane_b32 v253, s6, 42
	v_mov_b32_e32 v205, 0xfffe4000
	v_mov_b32_e32 v162, 0xfffe2000
	v_writelane_b32 v253, s7, 43
	s_add_u32 s6, s92, 0x23080600
	s_addc_u32 s7, s93, 0
	v_writelane_b32 v253, s6, 44
	v_mov_b32_e32 v163, 0xb0
	v_mov_b32_e32 v208, 0x47
	v_writelane_b32 v253, s7, 45
	s_add_u32 s6, s92, 0x23080700
	s_addc_u32 s7, s93, 0
	v_writelane_b32 v253, s6, 46
	v_mov_b32_e32 v209, 0x4f
	v_mov_b32_e32 v210, 0x57
	v_writelane_b32 v253, s7, 47
	s_add_u32 s6, s92, 0x23080800
	s_addc_u32 s7, s93, 0
	v_writelane_b32 v253, s6, 48
	v_mov_b32_e32 v211, 0x5f
	v_mov_b32_e32 v212, 0x67
	v_writelane_b32 v253, s7, 49
	s_add_u32 s6, s92, 0x23080900
	s_addc_u32 s7, s93, 0
	v_writelane_b32 v253, s6, 50
	v_mov_b32_e32 v213, 0x6f
	v_mov_b32_e32 v214, 0x77
	v_writelane_b32 v253, s7, 51
	s_add_u32 s6, s92, 0x23080a00
	s_addc_u32 s7, s93, 0
	v_writelane_b32 v253, s6, 52
	v_mov_b32_e32 v215, 0x7f
	s_movk_i32 s15, 0x2c00
	v_writelane_b32 v253, s7, 53
	s_add_u32 s6, s92, 0x23080b00
	s_addc_u32 s7, s93, 0
	v_writelane_b32 v253, s6, 54
	s_mov_b64 s[38:39], 0x80
	s_mov_b32 s30, 0xbfb8aa3b
	v_writelane_b32 v253, s7, 55
	s_add_u32 s6, s92, 0x23080c00
	s_addc_u32 s7, s93, 0
	v_writelane_b32 v253, s6, 56
	s_mov_b32 s72, 0
	s_nop 0
	v_writelane_b32 v253, s7, 57
	s_add_u32 s6, s92, 0x23080d00
	s_addc_u32 s7, s93, 0
	v_writelane_b32 v253, s6, 58
	s_nop 1
	v_writelane_b32 v253, s7, 59
	s_add_u32 s6, s92, 0x23080e00
	s_addc_u32 s7, s93, 0
	v_writelane_b32 v253, s6, 60
	s_nop 1
	v_writelane_b32 v253, s7, 61
	s_add_u32 s6, s92, 0x23080f00
	s_addc_u32 s7, s93, 0
	v_writelane_b32 v253, s6, 62
	s_nop 1
	v_writelane_b32 v253, s7, 63
	s_add_u32 s6, s92, 0x23081000
	s_addc_u32 s7, s93, 0
	v_writelane_b32 v254, s6, 0
	v_readlane_b32 s3, v253, 10
	s_nop 0
	v_writelane_b32 v254, s7, 1
	s_add_u32 s6, s92, 0x23081100
	s_addc_u32 s7, s93, 0
	v_writelane_b32 v254, s6, 2
	s_nop 1
	v_writelane_b32 v254, s7, 3
	s_add_u32 s6, s92, 0x23081200
	s_addc_u32 s7, s93, 0
	v_writelane_b32 v254, s6, 4
	s_nop 1
	v_writelane_b32 v254, s7, 5
	s_add_u32 s6, s92, 0x23081300
	s_addc_u32 s7, s93, 0
	v_writelane_b32 v254, s6, 6
; DI unsigned xb_ld(unsigned* p)              { return __hip_atomic_load(p, __ATOMIC_RELAXED, __HIP_MEMORY_SCOPE_AGENT); }
; DI void convert_range(const Args& a, LAS unsigned char* lds, int lo_, int hi_, int blk, int nblk, int wave, int lane, bool with_x) {
;     const int chunk = (((hi_ - lo_) + nblk - 1) / nblk + 7) & ~7;
;     const int lo = lo_ + blk * chunk - wave, hi = (lo_ + (blk + 1) * chunk) < hi_ ? (lo_ + (blk + 1) * chunk) : hi_;
; DI void xcd_barrier_complete(unsigned* bar, unsigned x, unsigned& nloc, unsigned& nx) {
;     const unsigned G = gridDim.x * gridDim.y * gridDim.z;
;     unsigned sum, cnt, mine, sp = 0u;
;     for (;;) {
;         sum = 0u; cnt = 0u; mine = 0u;
; #pragma unroll
;         for (unsigned j = 0; j < 16; ++j) { const unsigned c = xb_ld(&bar[XB_XCNT(j)]); sum += c; cnt += (c > 0u) ? 1u : 0u; mine = (j == x) ? c : mine; }
	s_cmp_eq_u32 s3, 15
	s_nop 0
	v_writelane_b32 v254, s7, 7
	s_cselect_b64 s[6:7], -1, 0
	v_writelane_b32 v254, s6, 8
	s_cmp_eq_u32 s3, 14
	s_nop 0
	v_writelane_b32 v254, s7, 9
	s_cselect_b64 s[6:7], -1, 0
	v_writelane_b32 v254, s6, 10
	s_cmp_eq_u32 s3, 13
	s_nop 0
	v_writelane_b32 v254, s7, 11
	s_cselect_b64 s[6:7], -1, 0
	v_writelane_b32 v254, s6, 12
	s_cmp_eq_u32 s3, 12
	s_nop 0
	v_writelane_b32 v254, s7, 13
	s_cselect_b64 s[6:7], -1, 0
	v_writelane_b32 v254, s6, 14
	s_cmp_eq_u32 s3, 11
	s_nop 0
	v_writelane_b32 v254, s7, 15
	s_cselect_b64 s[6:7], -1, 0
	v_writelane_b32 v254, s6, 16
	s_cmp_eq_u32 s3, 10
	s_nop 0
	v_writelane_b32 v254, s7, 17
	s_cselect_b64 s[6:7], -1, 0
	v_writelane_b32 v254, s6, 18
	s_cmp_eq_u32 s3, 9
	s_nop 0
	v_writelane_b32 v254, s7, 19
	s_cselect_b64 s[6:7], -1, 0
	v_writelane_b32 v254, s6, 20
	s_cmp_eq_u32 s3, 8
	s_nop 0
	v_writelane_b32 v254, s7, 21
	s_cselect_b64 s[6:7], -1, 0
	v_writelane_b32 v254, s6, 22
	s_cmp_eq_u32 s3, 7
	s_nop 0
	v_writelane_b32 v254, s7, 23
	s_cselect_b64 s[6:7], -1, 0
	v_writelane_b32 v254, s6, 24
	s_cmp_eq_u32 s3, 6
	s_nop 0
	v_writelane_b32 v254, s7, 25
	s_cselect_b64 s[6:7], -1, 0
	v_writelane_b32 v254, s6, 26
	s_cmp_eq_u32 s3, 5
	s_nop 0
	v_writelane_b32 v254, s7, 27
	s_cselect_b64 s[6:7], -1, 0
	v_writelane_b32 v254, s6, 28
	s_cmp_eq_u32 s3, 4
	s_nop 0
	v_writelane_b32 v254, s7, 29
	s_cselect_b64 s[6:7], -1, 0
	v_writelane_b32 v254, s6, 30
	s_cmp_eq_u32 s3, 3
	s_nop 0
	v_writelane_b32 v254, s7, 31
	s_cselect_b64 s[6:7], -1, 0
	v_writelane_b32 v254, s6, 32
	s_cmp_eq_u32 s3, 2
	s_nop 0
	v_writelane_b32 v254, s7, 33
	s_cselect_b64 s[6:7], -1, 0
	v_writelane_b32 v254, s6, 34
	s_cmp_eq_u32 s3, 1
	s_nop 0
	v_writelane_b32 v254, s7, 35
	s_cselect_b64 s[6:7], -1, 0
	v_writelane_b32 v254, s6, 36
	s_cmp_eq_u32 s3, 0
	s_nop 0
	v_writelane_b32 v254, s7, 37
	s_cselect_b64 s[6:7], -1, 0
	s_lshl_b32 s3, s3, 8
	s_add_u32 s3, s18, s3
	v_writelane_b32 v254, s6, 38
	s_addc_u32 s5, s19, 0
	s_nop 0
	v_writelane_b32 v254, s7, 39
	s_add_u32 s6, s3, 0x1400
	s_addc_u32 s7, s5, 0
	v_writelane_b32 v254, s6, 40
	s_nop 1
	v_writelane_b32 v254, s7, 41
	s_add_u32 s6, s3, 0x2400
	s_addc_u32 s7, s5, 0
	v_writelane_b32 v254, s6, 42
	s_nop 1
	v_writelane_b32 v254, s7, 43
	s_add_u32 s6, s92, 0x23083400
	s_addc_u32 s7, s93, 0
	v_writelane_b32 v254, s6, 44
	s_nop 1
	v_writelane_b32 v254, s7, 45
	s_add_u32 s6, s92, 0x23083500
	s_addc_u32 s7, s93, 0
	s_abs_i32 s3, s10
	v_cvt_f32_u32_e32 v1, s3
	v_writelane_b32 v254, s6, 46
	s_sub_i32 s5, 0, s3
	v_rcp_iflag_f32_e32 v1, v1
	v_writelane_b32 v254, s7, 47
	v_writelane_b32 v254, s8, 48
	v_mul_f32_e32 v1, 0x4f7ffffe, v1
	v_cvt_u32_f32_e32 v1, v1
	v_writelane_b32 v254, s9, 49
	s_and_b64 s[8:9], s[16:17], s[8:9]
	v_writelane_b32 v254, s8, 50
	v_readfirstlane_b32 s6, v1
	s_mul_i32 s5, s5, s6
	s_mul_hi_u32 s5, s6, s5
	s_add_i32 s6, s6, s5
	s_abs_i32 s5, s4
	s_mul_hi_u32 s6, s5, s6
	s_mul_i32 s7, s6, s3
	s_sub_i32 s5, s5, s7
	s_xor_b32 s4, s4, s10
	v_writelane_b32 v254, s9, 51
	s_ashr_i32 s4, s4, 31
	s_add_i32 s7, s6, 1
	s_sub_i32 s8, s5, s3
	s_cmp_ge_u32 s5, s3
	s_cselect_b32 s6, s7, s6
	s_cselect_b32 s5, s8, s5
	s_add_i32 s7, s6, 1
	v_lshrrev_b32_e32 v1, 20, v0
	v_lshrrev_b32_e32 v0, 10, v0
	s_cmp_ge_u32 s5, s3
	v_or_b32_e32 v0, v0, v1
	s_movk_i32 s3, 0x3ff
	v_and_or_b32 v0, v0, s3, v188
	s_cselect_b32 s3, s7, s6
	s_xor_b32 s3, s3, s4
	s_sub_i32 s3, s3, s4
	s_add_i32 s3, s3, 7
	s_and_b32 s3, s3, -8
	s_mul_i32 s4, s3, s2
	s_add_i32 s3, s4, s3
	s_min_i32 s14, s3, 0x2540
	s_lshl_b32 s3, s10, 12
	v_writelane_b32 v254, s4, 52
	s_add_i32 s3, s3, 0xfffe0000
	v_writelane_b32 v254, s3, 53
	s_add_u32 s3, s92, 0x18080080
	v_writelane_b32 v254, s3, 54
	s_addc_u32 s3, s93, 0
	v_writelane_b32 v254, s3, 55
	s_add_u32 s3, s92, 0x100
	v_writelane_b32 v254, s3, 56
	s_addc_u32 s3, s93, 0
	v_writelane_b32 v254, s3, 57
	s_add_i32 s3, 0, 0x23040
	v_writelane_b32 v254, s3, 58
	s_add_i32 s3, 0, 0x23fc0
	v_writelane_b32 v254, s3, 59
	s_add_i32 s3, 0, 0x23fc4
	v_writelane_b32 v254, s3, 60
	s_add_i32 s3, 0, 0x23fc8
	v_writelane_b32 v254, s3, 61
	v_cmp_eq_u32_e64 s[4:5], 0, v188
	s_lshl_b64 s[54:55], s[10:11], 13
	s_nop 0
	v_writelane_b32 v254, s4, 62
	s_nop 1
	v_writelane_b32 v254, s5, 63
	v_cmp_eq_u32_e64 s[4:5], 0, v0
	s_nop 1
	v_writelane_b32 v255, s4, 0
	s_nop 1
	v_writelane_b32 v255, s5, 1
	v_writelane_b32 v255, s10, 2
	s_mov_b64 s[4:5], 0
	s_lshl_b64 s[34:35], s[10:11], 12
	v_writelane_b32 v255, s11, 3
	v_writelane_b32 v255, s4, 4
	s_nop 1
	v_writelane_b32 v255, s5, 5
	v_writelane_b32 v255, s84, 6
	s_nop 1
	v_writelane_b32 v255, s85, 7
	v_writelane_b32 v255, s86, 8
	s_nop 1
	v_writelane_b32 v255, s87, 9
	v_writelane_b32 v255, s96, 10
	s_nop 1
	v_writelane_b32 v255, s97, 11
	v_writelane_b32 v255, s98, 12
	s_nop 1
	v_writelane_b32 v255, s99, 13
	v_writelane_b32 v255, s54, 14
	s_nop 1
	v_writelane_b32 v255, s55, 15
	s_branch .LBB0_12

; #define LAS __attribute__((address_space(3)))
; DI void convert_dyn(const Args& a, LAS unsigned char* lds, int lo, int hi, unsigned* ctr, int wave, int lane) {
;     LAS float* scr = (LAS float*)(lds + wave * 16640);
; __global__ void __launch_bounds__(NTHREADS, 2) mega_fwd(Args a) {
;     ...
;             const bool split = (fidx < 3) && (G > GEMM_G_UP);
;             const int cv_lo = (fidx == 0) ? CV_S0 : (fidx == 1) ? CV_S1 : CV_S2, cv_hi = (fidx == 0) ? CV_S1 : (fidx == 1) ? CV_S2 : CV_NITEMS;
;             unsigned* cv_ctr = (unsigned*)(ws + WS_CTL) + 16384 + 64 * (1 + fidx);
.LBB0_255:
	s_cmpk_gt_i32 s2, 0xcf
	s_cselect_b64 s[4:5], -1, 0
	s_and_b64 s[0:1], s[0:1], s[4:5]
	s_andn2_b64 vcc, exec, s[0:1]
	s_cbranch_vccnz .LBB0_433
	s_cmp_eq_u32 s83, 1
	s_movk_i32 s0, 0x4e40
	s_mov_b32 s1, 0xa040
	s_cselect_b32 s0, s0, 0x7740
	s_cselect_b32 s1, 0x7740, s1
	s_cmp_eq_u32 s83, 0
	s_cselect_b32 s3, 0x2540, s0
	s_cselect_b32 s12, 0x4e40, s1
	s_lshl_b32 s0, s83, 6
	s_mov_b32 s1, s72
	s_lshl_b64 s[0:1], s[0:1], 2
	v_readlane_b32 s4, v253, 27
	v_readlane_b32 s5, v253, 28
	s_add_u32 s0, s4, s0
	s_waitcnt vmcnt(0)
	v_mov_b32 v0, v188
	s_addc_u32 s1, s5, s1
	v_readfirstlane_b32 s4, v0
	v_and_b32_e32 v1, 63, v0
	s_lshr_b32 s4, s4, 6
	s_mulk_i32 s4, 0x4100
	v_cmp_eq_u32_e64 s[40:41], 0, v1
	v_lshlrev_b32_e32 v1, 2, v0
	s_add_i32 s4, s4, 0
	s_waitcnt vmcnt(0)
	v_bfe_u32 v135, v0, 4, 2
	v_and_b32_e32 v134, 60, v1
	v_and_b32_e32 v3, 7, v0
	v_bfe_u32 v137, v0, 3, 3
	v_lshl_add_u32 v1, v134, 2, s4
	v_mul_u32_u24_e32 v2, 0x104, v135
	v_mul_u32_u24_e32 v0, 0x820, v3
	v_lshlrev_b32_e32 v4, 2, v137
	v_lshlrev_b32_e32 v136, 3, v3
	v_add3_u32 v140, s4, v0, v4
	v_or_b32_e32 v141, 8, v137
	v_or_b32_e32 v142, 16, v137
	v_or_b32_e32 v143, 24, v137
	v_or_b32_e32 v144, 32, v137
	v_or_b32_e32 v145, 40, v137
	v_or_b32_e32 v146, 48, v137
	v_or_b32_e32 v147, 56, v137
	v_lshl_add_u32 v148, v3, 5, s4
	v_mul_u32_u24_e32 v149, 0x104, v137
	v_add_u32_e32 v150, v1, v2
	s_branch .LBB0_259
